# k13
# speedup vs baseline: 1.1201x; 1.0042x over previous
.Lgl1_entry:
	s_mov_b64 s[82:83], exec
	v_readlane_b32 s4, v254, 40
	v_readlane_b32 s5, v254, 41
	v_readlane_b32 s6, v255, 15
	v_readlane_b32 s7, v254, 21
	s_nop 4
	s_load_dword s8, s[4:5], 0x0
	v_mbcnt_lo_u32_b32 v0, -1, 0
	v_mbcnt_hi_u32_b32 v0, -1, v0
	v_readlane_b32 s9, v255, 48
	v_readlane_b32 s10, v255, 52
	v_readlane_b32 s11, v255, 53
	v_readlane_b32 s12, v255, 54
	v_readlane_b32 s13, v255, 55
	v_readlane_b32 s14, v255, 50
	v_readlane_b32 s15, v255, 51
	v_lshlrev_b32_e32 v1, 6, v0
	v_lshlrev_b32_e32 v2, 5, v0
	v_lshlrev_b32_e32 v3, 2, v0
	v_xor_b32_e32 v4, 0x4, v3
	v_xor_b32_e32 v5, 0x8, v3
	v_xor_b32_e32 v6, 0x10, v3
	v_xor_b32_e32 v7, 0x20, v3
	v_xor_b32_e32 v8, 0x40, v3
	v_xor_b32_e32 v9, 0x80, v3
	v_mov_b32_e32 v10, 0x3727c5ac
	s_and_b32 s9, s9, 0xff
	s_lshl_b32 s9, s9, 13
	s_add_u32 s10, s10, s9
	s_addc_u32 s11, s11, 0
	s_add_u32 s12, s12, s9
	s_addc_u32 s13, s13, 0
	global_load_dwordx4 v[16:19], v1, s[10:11]
	global_load_dwordx4 v[20:23], v1, s[10:11] offset:16
	global_load_dwordx4 v[24:27], v1, s[10:11] offset:32
	global_load_dwordx4 v[28:31], v1, s[10:11] offset:48
	global_load_dwordx4 v[32:35], v1, s[12:13]
	global_load_dwordx4 v[36:39], v1, s[12:13] offset:16
	global_load_dwordx4 v[40:43], v1, s[12:13] offset:32
	global_load_dwordx4 v[44:47], v1, s[12:13] offset:48
	v_add_u32_e32 v49, 0x1000, v1
	v_add_u32_e32 v53, 0x800, v2
	v_add_u32_e32 v50, 0x2000, v1
	v_add_u32_e32 v54, 0x1000, v2
	v_add_u32_e32 v51, 0x3000, v1
	v_add_u32_e32 v55, 0x1800, v2
	v_mov_b32_e32 v48, v1
	v_mov_b32_e32 v52, v2
	s_lshl_b32 s6, s6, 2
	s_lshr_b32 s7, s7, 6
	s_add_u32 s6, s6, s7
	s_lshl_b32 s22, s6, 2
	s_waitcnt lgkmcnt(0)
	s_lshl_b32 s26, s8, 4
	s_add_u32 s16, s92, 0xc100000
	s_addc_u32 s17, s93, 0
	s_add_u32 s18, s92, 0x8100000
	s_addc_u32 s19, s93, 0
	s_add_u32 s14, s92, 0x2a100000
	s_addc_u32 s15, s93, 0
	s_cmp_ge_u32 s22, 0x8000
	s_cbranch_scc1 .Lgl1_done
	s_lshl_b32 s30, s22, 12
	s_add_u32 s40, s16, s30
	s_addc_u32 s41, s17, 0
	global_load_dwordx4 v[64:67], v48, s[40:41]
	global_load_dwordx4 v[68:71], v48, s[40:41] offset:16
	global_load_dwordx4 v[72:75], v48, s[40:41] offset:32
	global_load_dwordx4 v[76:79], v48, s[40:41] offset:48
	global_load_dwordx4 v[80:83], v49, s[40:41]
	global_load_dwordx4 v[84:87], v49, s[40:41] offset:16
	global_load_dwordx4 v[88:91], v49, s[40:41] offset:32
	global_load_dwordx4 v[92:95], v49, s[40:41] offset:48
	global_load_dwordx4 v[96:99], v50, s[40:41]
	global_load_dwordx4 v[100:103], v50, s[40:41] offset:16
	global_load_dwordx4 v[104:107], v50, s[40:41] offset:32
	global_load_dwordx4 v[108:111], v50, s[40:41] offset:48
	global_load_dwordx4 v[112:115], v51, s[40:41]
	global_load_dwordx4 v[116:119], v51, s[40:41] offset:16
	global_load_dwordx4 v[120:123], v51, s[40:41] offset:32
	global_load_dwordx4 v[124:127], v51, s[40:41] offset:48
	s_waitcnt vmcnt(16)
.Lgl1_loop:
	s_add_u32 s42, s22, s26
	s_min_u32 s42, s42, 0x7ffc
	s_lshl_b32 s30, s42, 12
	s_add_u32 s40, s16, s30
	s_addc_u32 s41, s17, 0
	global_load_dwordx4 v[128:131], v48, s[40:41]
	global_load_dwordx4 v[132:135], v48, s[40:41] offset:16
	global_load_dwordx4 v[136:139], v48, s[40:41] offset:32
	global_load_dwordx4 v[140:143], v48, s[40:41] offset:48
	global_load_dwordx4 v[144:147], v49, s[40:41]
	global_load_dwordx4 v[148:151], v49, s[40:41] offset:16
	global_load_dwordx4 v[152:155], v49, s[40:41] offset:32
	global_load_dwordx4 v[156:159], v49, s[40:41] offset:48
	global_load_dwordx4 v[160:163], v50, s[40:41]
	global_load_dwordx4 v[164:167], v50, s[40:41] offset:16
	global_load_dwordx4 v[168:171], v50, s[40:41] offset:32
	global_load_dwordx4 v[172:175], v50, s[40:41] offset:48
	global_load_dwordx4 v[176:179], v51, s[40:41]
	global_load_dwordx4 v[180:183], v51, s[40:41] offset:16
	global_load_dwordx4 v[184:187], v51, s[40:41] offset:32
	global_load_dwordx4 v[188:191], v51, s[40:41] offset:48
	s_lshl_b32 s30, s22, 12
	s_add_u32 s64, s14, s30
	s_addc_u32 s65, s15, 0
	s_lshl_b32 s30, s22, 11
	s_add_u32 s66, s18, s30
	s_addc_u32 s67, s19, 0
	s_waitcnt vmcnt(28)
	v_add_f32_e32 v56, v64, v65
	v_add_f32_e32 v56, v66, v56
	v_add_f32_e32 v56, v67, v56
	v_add_f32_e32 v56, v68, v56
	v_add_f32_e32 v56, v69, v56
	v_add_f32_e32 v56, v70, v56
	v_add_f32_e32 v56, v71, v56
	v_add_f32_e32 v56, v72, v56
	v_add_f32_e32 v56, v73, v56
	v_add_f32_e32 v56, v74, v56
	v_add_f32_e32 v56, v75, v56
	v_add_f32_e32 v56, v76, v56
	v_add_f32_e32 v56, v77, v56
	v_add_f32_e32 v56, v78, v56
	v_add_f32_e32 v56, v79, v56
	s_waitcnt vmcnt(24)
	v_add_f32_e32 v57, v80, v81
	v_add_f32_e32 v57, v82, v57
	v_add_f32_e32 v57, v83, v57
	v_add_f32_e32 v57, v84, v57
	v_add_f32_e32 v57, v85, v57
	v_add_f32_e32 v57, v86, v57
	v_add_f32_e32 v57, v87, v57
	v_add_f32_e32 v57, v88, v57
	v_add_f32_e32 v57, v89, v57
	v_add_f32_e32 v57, v90, v57
	v_add_f32_e32 v57, v91, v57
	v_add_f32_e32 v57, v92, v57
	v_add_f32_e32 v57, v93, v57
	v_add_f32_e32 v57, v94, v57
	v_add_f32_e32 v57, v95, v57
	s_waitcnt vmcnt(20)
	v_add_f32_e32 v58, v96, v97
	v_add_f32_e32 v58, v98, v58
	v_add_f32_e32 v58, v99, v58
	v_add_f32_e32 v58, v100, v58
	v_add_f32_e32 v58, v101, v58
	v_add_f32_e32 v58, v102, v58
	v_add_f32_e32 v58, v103, v58
	v_add_f32_e32 v58, v104, v58
	v_add_f32_e32 v58, v105, v58
	v_add_f32_e32 v58, v106, v58
	v_add_f32_e32 v58, v107, v58
	v_add_f32_e32 v58, v108, v58
	v_add_f32_e32 v58, v109, v58
	v_add_f32_e32 v58, v110, v58
	v_add_f32_e32 v58, v111, v58
	s_waitcnt vmcnt(16)
	v_add_f32_e32 v59, v112, v113
	v_add_f32_e32 v59, v114, v59
	v_add_f32_e32 v59, v115, v59
	v_add_f32_e32 v59, v116, v59
	v_add_f32_e32 v59, v117, v59
	v_add_f32_e32 v59, v118, v59
	v_add_f32_e32 v59, v119, v59
	v_add_f32_e32 v59, v120, v59
	v_add_f32_e32 v59, v121, v59
	v_add_f32_e32 v59, v122, v59
	v_add_f32_e32 v59, v123, v59
	v_add_f32_e32 v59, v124, v59
	v_add_f32_e32 v59, v125, v59
	v_add_f32_e32 v59, v126, v59
	v_add_f32_e32 v59, v127, v59
	ds_bpermute_b32 v60, v4, v56
	ds_bpermute_b32 v61, v4, v57
	ds_bpermute_b32 v62, v4, v58
	ds_bpermute_b32 v63, v4, v59
	s_waitcnt lgkmcnt(3)
	v_add_f32_e32 v56, v56, v60
	s_waitcnt lgkmcnt(2)
	v_add_f32_e32 v57, v57, v61
	s_waitcnt lgkmcnt(1)
	v_add_f32_e32 v58, v58, v62
	s_waitcnt lgkmcnt(0)
	v_add_f32_e32 v59, v59, v63
	ds_bpermute_b32 v60, v5, v56
	ds_bpermute_b32 v61, v5, v57
	ds_bpermute_b32 v62, v5, v58
	ds_bpermute_b32 v63, v5, v59
	s_waitcnt lgkmcnt(3)
	v_add_f32_e32 v56, v56, v60
	s_waitcnt lgkmcnt(2)
	v_add_f32_e32 v57, v57, v61
	s_waitcnt lgkmcnt(1)
	v_add_f32_e32 v58, v58, v62
	s_waitcnt lgkmcnt(0)
	v_add_f32_e32 v59, v59, v63
	ds_bpermute_b32 v60, v6, v56
	ds_bpermute_b32 v61, v6, v57
	ds_bpermute_b32 v62, v6, v58
	ds_bpermute_b32 v63, v6, v59
	s_waitcnt lgkmcnt(3)
	v_add_f32_e32 v56, v56, v60
	s_waitcnt lgkmcnt(2)
	v_add_f32_e32 v57, v57, v61
	s_waitcnt lgkmcnt(1)
	v_add_f32_e32 v58, v58, v62
	s_waitcnt lgkmcnt(0)
	v_add_f32_e32 v59, v59, v63
	ds_bpermute_b32 v60, v7, v56
	ds_bpermute_b32 v61, v7, v57
	ds_bpermute_b32 v62, v7, v58
	ds_bpermute_b32 v63, v7, v59
	s_waitcnt lgkmcnt(3)
	v_add_f32_e32 v56, v56, v60
	s_waitcnt lgkmcnt(2)
	v_add_f32_e32 v57, v57, v61
	s_waitcnt lgkmcnt(1)
	v_add_f32_e32 v58, v58, v62
	s_waitcnt lgkmcnt(0)
	v_add_f32_e32 v59, v59, v63
	ds_bpermute_b32 v60, v8, v56
	ds_bpermute_b32 v61, v8, v57
	ds_bpermute_b32 v62, v8, v58
	ds_bpermute_b32 v63, v8, v59
	s_waitcnt lgkmcnt(3)
	v_add_f32_e32 v56, v56, v60
	s_waitcnt lgkmcnt(2)
	v_add_f32_e32 v57, v57, v61
	s_waitcnt lgkmcnt(1)
	v_add_f32_e32 v58, v58, v62
	s_waitcnt lgkmcnt(0)
	v_add_f32_e32 v59, v59, v63
	ds_bpermute_b32 v60, v9, v56
	ds_bpermute_b32 v61, v9, v57
	ds_bpermute_b32 v62, v9, v58
	ds_bpermute_b32 v63, v9, v59
	s_waitcnt lgkmcnt(3)
	v_add_f32_e32 v56, v56, v60
	s_waitcnt lgkmcnt(2)
	v_add_f32_e32 v57, v57, v61
	s_waitcnt lgkmcnt(1)
	v_add_f32_e32 v58, v58, v62
	s_waitcnt lgkmcnt(0)
	v_add_f32_e32 v59, v59, v63
	v_mul_f32_e32 v60, 0x3a800000, v56
	v_sub_f32_e32 v64, v64, v60
	v_sub_f32_e32 v65, v65, v60
	v_sub_f32_e32 v66, v66, v60
	v_sub_f32_e32 v67, v67, v60
	v_sub_f32_e32 v68, v68, v60
	v_sub_f32_e32 v69, v69, v60
	v_sub_f32_e32 v70, v70, v60
	v_sub_f32_e32 v71, v71, v60
	v_sub_f32_e32 v72, v72, v60
	v_sub_f32_e32 v73, v73, v60
	v_sub_f32_e32 v74, v74, v60
	v_sub_f32_e32 v75, v75, v60
	v_sub_f32_e32 v76, v76, v60
	v_sub_f32_e32 v77, v77, v60
	v_sub_f32_e32 v78, v78, v60
	v_sub_f32_e32 v79, v79, v60
	v_mul_f32_e32 v56, v64, v64
	v_fmac_f32_e32 v56, v65, v65
	v_fmac_f32_e32 v56, v66, v66
	v_fmac_f32_e32 v56, v67, v67
	v_fmac_f32_e32 v56, v68, v68
	v_fmac_f32_e32 v56, v69, v69
	v_fmac_f32_e32 v56, v70, v70
	v_fmac_f32_e32 v56, v71, v71
	v_fmac_f32_e32 v56, v72, v72
	v_fmac_f32_e32 v56, v73, v73
	v_fmac_f32_e32 v56, v74, v74
	v_fmac_f32_e32 v56, v75, v75
	v_fmac_f32_e32 v56, v76, v76
	v_fmac_f32_e32 v56, v77, v77
	v_fmac_f32_e32 v56, v78, v78
	v_fmac_f32_e32 v56, v79, v79
	v_mul_f32_e32 v61, 0x3a800000, v57
	v_sub_f32_e32 v80, v80, v61
	v_sub_f32_e32 v81, v81, v61
	v_sub_f32_e32 v82, v82, v61
	v_sub_f32_e32 v83, v83, v61
	v_sub_f32_e32 v84, v84, v61
	v_sub_f32_e32 v85, v85, v61
	v_sub_f32_e32 v86, v86, v61
	v_sub_f32_e32 v87, v87, v61
	v_sub_f32_e32 v88, v88, v61
	v_sub_f32_e32 v89, v89, v61
	v_sub_f32_e32 v90, v90, v61
	v_sub_f32_e32 v91, v91, v61
	v_sub_f32_e32 v92, v92, v61
	v_sub_f32_e32 v93, v93, v61
	v_sub_f32_e32 v94, v94, v61
	v_sub_f32_e32 v95, v95, v61
	v_mul_f32_e32 v57, v80, v80
	v_fmac_f32_e32 v57, v81, v81
	v_fmac_f32_e32 v57, v82, v82
	v_fmac_f32_e32 v57, v83, v83
	v_fmac_f32_e32 v57, v84, v84
	v_fmac_f32_e32 v57, v85, v85
	v_fmac_f32_e32 v57, v86, v86
	v_fmac_f32_e32 v57, v87, v87
	v_fmac_f32_e32 v57, v88, v88
	v_fmac_f32_e32 v57, v89, v89
	v_fmac_f32_e32 v57, v90, v90
	v_fmac_f32_e32 v57, v91, v91
	v_fmac_f32_e32 v57, v92, v92
	v_fmac_f32_e32 v57, v93, v93
	v_fmac_f32_e32 v57, v94, v94
	v_fmac_f32_e32 v57, v95, v95
	v_mul_f32_e32 v62, 0x3a800000, v58
	v_sub_f32_e32 v96, v96, v62
	v_sub_f32_e32 v97, v97, v62
	v_sub_f32_e32 v98, v98, v62
	v_sub_f32_e32 v99, v99, v62
	v_sub_f32_e32 v100, v100, v62
	v_sub_f32_e32 v101, v101, v62
	v_sub_f32_e32 v102, v102, v62
	v_sub_f32_e32 v103, v103, v62
	v_sub_f32_e32 v104, v104, v62
	v_sub_f32_e32 v105, v105, v62
	v_sub_f32_e32 v106, v106, v62
	v_sub_f32_e32 v107, v107, v62
	v_sub_f32_e32 v108, v108, v62
	v_sub_f32_e32 v109, v109, v62
	v_sub_f32_e32 v110, v110, v62
	v_sub_f32_e32 v111, v111, v62
	v_mul_f32_e32 v58, v96, v96
	v_fmac_f32_e32 v58, v97, v97
	v_fmac_f32_e32 v58, v98, v98
	v_fmac_f32_e32 v58, v99, v99
	v_fmac_f32_e32 v58, v100, v100
	v_fmac_f32_e32 v58, v101, v101
	v_fmac_f32_e32 v58, v102, v102
	v_fmac_f32_e32 v58, v103, v103
	v_fmac_f32_e32 v58, v104, v104
	v_fmac_f32_e32 v58, v105, v105
	v_fmac_f32_e32 v58, v106, v106
	v_fmac_f32_e32 v58, v107, v107
	v_fmac_f32_e32 v58, v108, v108
	v_fmac_f32_e32 v58, v109, v109
	v_fmac_f32_e32 v58, v110, v110
	v_fmac_f32_e32 v58, v111, v111
	v_mul_f32_e32 v63, 0x3a800000, v59
	v_sub_f32_e32 v112, v112, v63
	v_sub_f32_e32 v113, v113, v63
	v_sub_f32_e32 v114, v114, v63
	v_sub_f32_e32 v115, v115, v63
	v_sub_f32_e32 v116, v116, v63
	v_sub_f32_e32 v117, v117, v63
	v_sub_f32_e32 v118, v118, v63
	v_sub_f32_e32 v119, v119, v63
	v_sub_f32_e32 v120, v120, v63
	v_sub_f32_e32 v121, v121, v63
	v_sub_f32_e32 v122, v122, v63
	v_sub_f32_e32 v123, v123, v63
	v_sub_f32_e32 v124, v124, v63
	v_sub_f32_e32 v125, v125, v63
	v_sub_f32_e32 v126, v126, v63
	v_sub_f32_e32 v127, v127, v63
	v_mul_f32_e32 v59, v112, v112
	v_fmac_f32_e32 v59, v113, v113
	v_fmac_f32_e32 v59, v114, v114
	v_fmac_f32_e32 v59, v115, v115
	v_fmac_f32_e32 v59, v116, v116
	v_fmac_f32_e32 v59, v117, v117
	v_fmac_f32_e32 v59, v118, v118
	v_fmac_f32_e32 v59, v119, v119
	v_fmac_f32_e32 v59, v120, v120
	v_fmac_f32_e32 v59, v121, v121
	v_fmac_f32_e32 v59, v122, v122
	v_fmac_f32_e32 v59, v123, v123
	v_fmac_f32_e32 v59, v124, v124
	v_fmac_f32_e32 v59, v125, v125
	v_fmac_f32_e32 v59, v126, v126
	v_fmac_f32_e32 v59, v127, v127
	ds_bpermute_b32 v60, v4, v56
	ds_bpermute_b32 v61, v4, v57
	ds_bpermute_b32 v62, v4, v58
	ds_bpermute_b32 v63, v4, v59
	s_waitcnt lgkmcnt(3)
	v_add_f32_e32 v56, v56, v60
	s_waitcnt lgkmcnt(2)
	v_add_f32_e32 v57, v57, v61
	s_waitcnt lgkmcnt(1)
	v_add_f32_e32 v58, v58, v62
	s_waitcnt lgkmcnt(0)
	v_add_f32_e32 v59, v59, v63
	ds_bpermute_b32 v60, v5, v56
	ds_bpermute_b32 v61, v5, v57
	ds_bpermute_b32 v62, v5, v58
	ds_bpermute_b32 v63, v5, v59
	s_waitcnt lgkmcnt(3)
	v_add_f32_e32 v56, v56, v60
	s_waitcnt lgkmcnt(2)
	v_add_f32_e32 v57, v57, v61
	s_waitcnt lgkmcnt(1)
	v_add_f32_e32 v58, v58, v62
	s_waitcnt lgkmcnt(0)
	v_add_f32_e32 v59, v59, v63
	ds_bpermute_b32 v60, v6, v56
	ds_bpermute_b32 v61, v6, v57
	ds_bpermute_b32 v62, v6, v58
	ds_bpermute_b32 v63, v6, v59
	s_waitcnt lgkmcnt(3)
	v_add_f32_e32 v56, v56, v60
	s_waitcnt lgkmcnt(2)
	v_add_f32_e32 v57, v57, v61
	s_waitcnt lgkmcnt(1)
	v_add_f32_e32 v58, v58, v62
	s_waitcnt lgkmcnt(0)
	v_add_f32_e32 v59, v59, v63
	ds_bpermute_b32 v60, v7, v56
	ds_bpermute_b32 v61, v7, v57
	ds_bpermute_b32 v62, v7, v58
	ds_bpermute_b32 v63, v7, v59
	s_waitcnt lgkmcnt(3)
	v_add_f32_e32 v56, v56, v60
	s_waitcnt lgkmcnt(2)
	v_add_f32_e32 v57, v57, v61
	s_waitcnt lgkmcnt(1)
	v_add_f32_e32 v58, v58, v62
	s_waitcnt lgkmcnt(0)
	v_add_f32_e32 v59, v59, v63
	ds_bpermute_b32 v60, v8, v56
	ds_bpermute_b32 v61, v8, v57
	ds_bpermute_b32 v62, v8, v58
	ds_bpermute_b32 v63, v8, v59
	s_waitcnt lgkmcnt(3)
	v_add_f32_e32 v56, v56, v60
	s_waitcnt lgkmcnt(2)
	v_add_f32_e32 v57, v57, v61
	s_waitcnt lgkmcnt(1)
	v_add_f32_e32 v58, v58, v62
	s_waitcnt lgkmcnt(0)
	v_add_f32_e32 v59, v59, v63
	ds_bpermute_b32 v60, v9, v56
	ds_bpermute_b32 v61, v9, v57
	ds_bpermute_b32 v62, v9, v58
	ds_bpermute_b32 v63, v9, v59
	s_waitcnt lgkmcnt(3)
	v_add_f32_e32 v56, v56, v60
	s_waitcnt lgkmcnt(2)
	v_add_f32_e32 v57, v57, v61
	s_waitcnt lgkmcnt(1)
	v_add_f32_e32 v58, v58, v62
	s_waitcnt lgkmcnt(0)
	v_add_f32_e32 v59, v59, v63
	v_fmamk_f32 v56, v56, 0x3a800000, v10
	v_fmamk_f32 v57, v57, 0x3a800000, v10
	v_fmamk_f32 v58, v58, 0x3a800000, v10
	v_fmamk_f32 v59, v59, 0x3a800000, v10
	v_rsq_f32_e32 v56, v56
	v_rsq_f32_e32 v57, v57
	v_rsq_f32_e32 v58, v58
	v_rsq_f32_e32 v59, v59
	s_nop 1
	v_mul_f32_e32 v64, v64, v56
	v_mul_f32_e32 v65, v65, v56
	v_mul_f32_e32 v66, v66, v56
	v_mul_f32_e32 v67, v67, v56
	v_mul_f32_e32 v68, v68, v56
	v_mul_f32_e32 v69, v69, v56
	v_mul_f32_e32 v70, v70, v56
	v_mul_f32_e32 v71, v71, v56
	v_mul_f32_e32 v72, v72, v56
	v_mul_f32_e32 v73, v73, v56
	v_mul_f32_e32 v74, v74, v56
	v_mul_f32_e32 v75, v75, v56
	v_mul_f32_e32 v76, v76, v56
	v_mul_f32_e32 v77, v77, v56
	v_mul_f32_e32 v78, v78, v56
	v_mul_f32_e32 v79, v79, v56
	v_fma_f32 v64, v64, v16, v32
	v_fma_f32 v65, v65, v17, v33
	v_fma_f32 v66, v66, v18, v34
	v_fma_f32 v67, v67, v19, v35
	v_fma_f32 v68, v68, v20, v36
	v_fma_f32 v69, v69, v21, v37
	v_fma_f32 v70, v70, v22, v38
	v_fma_f32 v71, v71, v23, v39
	v_fma_f32 v72, v72, v24, v40
	v_fma_f32 v73, v73, v25, v41
	v_fma_f32 v74, v74, v26, v42
	v_fma_f32 v75, v75, v27, v43
	v_fma_f32 v76, v76, v28, v44
	v_fma_f32 v77, v77, v29, v45
	v_fma_f32 v78, v78, v30, v46
	v_fma_f32 v79, v79, v31, v47
	global_store_dwordx4 v48, v[64:67], s[64:65]
	global_store_dwordx4 v48, v[68:71], s[64:65] offset:16
	global_store_dwordx4 v48, v[72:75], s[64:65] offset:32
	global_store_dwordx4 v48, v[76:79], s[64:65] offset:48
	v_mul_f32_e32 v80, v80, v57
	v_mul_f32_e32 v81, v81, v57
	v_mul_f32_e32 v82, v82, v57
	v_mul_f32_e32 v83, v83, v57
	v_mul_f32_e32 v84, v84, v57
	v_mul_f32_e32 v85, v85, v57
	v_mul_f32_e32 v86, v86, v57
	v_mul_f32_e32 v87, v87, v57
	v_mul_f32_e32 v88, v88, v57
	v_mul_f32_e32 v89, v89, v57
	v_mul_f32_e32 v90, v90, v57
	v_mul_f32_e32 v91, v91, v57
	v_mul_f32_e32 v92, v92, v57
	v_mul_f32_e32 v93, v93, v57
	v_mul_f32_e32 v94, v94, v57
	v_mul_f32_e32 v95, v95, v57
	v_fma_f32 v80, v80, v16, v32
	v_fma_f32 v81, v81, v17, v33
	v_fma_f32 v82, v82, v18, v34
	v_fma_f32 v83, v83, v19, v35
	v_fma_f32 v84, v84, v20, v36
	v_fma_f32 v85, v85, v21, v37
	v_fma_f32 v86, v86, v22, v38
	v_fma_f32 v87, v87, v23, v39
	v_fma_f32 v88, v88, v24, v40
	v_fma_f32 v89, v89, v25, v41
	v_fma_f32 v90, v90, v26, v42
	v_fma_f32 v91, v91, v27, v43
	v_fma_f32 v92, v92, v28, v44
	v_fma_f32 v93, v93, v29, v45
	v_fma_f32 v94, v94, v30, v46
	v_fma_f32 v95, v95, v31, v47
	global_store_dwordx4 v49, v[80:83], s[64:65]
	global_store_dwordx4 v49, v[84:87], s[64:65] offset:16
	global_store_dwordx4 v49, v[88:91], s[64:65] offset:32
	global_store_dwordx4 v49, v[92:95], s[64:65] offset:48
	v_mul_f32_e32 v96, v96, v58
	v_mul_f32_e32 v97, v97, v58
	v_mul_f32_e32 v98, v98, v58
	v_mul_f32_e32 v99, v99, v58
	v_mul_f32_e32 v100, v100, v58
	v_mul_f32_e32 v101, v101, v58
	v_mul_f32_e32 v102, v102, v58
	v_mul_f32_e32 v103, v103, v58
	v_mul_f32_e32 v104, v104, v58
	v_mul_f32_e32 v105, v105, v58
	v_mul_f32_e32 v106, v106, v58
	v_mul_f32_e32 v107, v107, v58
	v_mul_f32_e32 v108, v108, v58
	v_mul_f32_e32 v109, v109, v58
	v_mul_f32_e32 v110, v110, v58
	v_mul_f32_e32 v111, v111, v58
	v_fma_f32 v96, v96, v16, v32
	v_fma_f32 v97, v97, v17, v33
	v_fma_f32 v98, v98, v18, v34
	v_fma_f32 v99, v99, v19, v35
	v_fma_f32 v100, v100, v20, v36
	v_fma_f32 v101, v101, v21, v37
	v_fma_f32 v102, v102, v22, v38
	v_fma_f32 v103, v103, v23, v39
	v_fma_f32 v104, v104, v24, v40
	v_fma_f32 v105, v105, v25, v41
	v_fma_f32 v106, v106, v26, v42
	v_fma_f32 v107, v107, v27, v43
	v_fma_f32 v108, v108, v28, v44
	v_fma_f32 v109, v109, v29, v45
	v_fma_f32 v110, v110, v30, v46
	v_fma_f32 v111, v111, v31, v47
	global_store_dwordx4 v50, v[96:99], s[64:65]
	global_store_dwordx4 v50, v[100:103], s[64:65] offset:16
	global_store_dwordx4 v50, v[104:107], s[64:65] offset:32
	global_store_dwordx4 v50, v[108:111], s[64:65] offset:48
	v_mul_f32_e32 v112, v112, v59
	v_mul_f32_e32 v113, v113, v59
	v_mul_f32_e32 v114, v114, v59
	v_mul_f32_e32 v115, v115, v59
	v_mul_f32_e32 v116, v116, v59
	v_mul_f32_e32 v117, v117, v59
	v_mul_f32_e32 v118, v118, v59
	v_mul_f32_e32 v119, v119, v59
	v_mul_f32_e32 v120, v120, v59
	v_mul_f32_e32 v121, v121, v59
	v_mul_f32_e32 v122, v122, v59
	v_mul_f32_e32 v123, v123, v59
	v_mul_f32_e32 v124, v124, v59
	v_mul_f32_e32 v125, v125, v59
	v_mul_f32_e32 v126, v126, v59
	v_mul_f32_e32 v127, v127, v59
	v_fma_f32 v112, v112, v16, v32
	v_fma_f32 v113, v113, v17, v33
	v_fma_f32 v114, v114, v18, v34
	v_fma_f32 v115, v115, v19, v35
	v_fma_f32 v116, v116, v20, v36
	v_fma_f32 v117, v117, v21, v37
	v_fma_f32 v118, v118, v22, v38
	v_fma_f32 v119, v119, v23, v39
	v_fma_f32 v120, v120, v24, v40
	v_fma_f32 v121, v121, v25, v41
	v_fma_f32 v122, v122, v26, v42
	v_fma_f32 v123, v123, v27, v43
	v_fma_f32 v124, v124, v28, v44
	v_fma_f32 v125, v125, v29, v45
	v_fma_f32 v126, v126, v30, v46
	v_fma_f32 v127, v127, v31, v47
	global_store_dwordx4 v51, v[112:115], s[64:65]
	global_store_dwordx4 v51, v[116:119], s[64:65] offset:16
	global_store_dwordx4 v51, v[120:123], s[64:65] offset:32
	global_store_dwordx4 v51, v[124:127], s[64:65] offset:48
	s_nop 1
	v_cvt_pk_bf16_f32 v192, v64, v65
	v_cvt_pk_bf16_f32 v193, v66, v67
	v_cvt_pk_bf16_f32 v194, v68, v69
	v_cvt_pk_bf16_f32 v195, v70, v71
	v_cvt_pk_bf16_f32 v196, v72, v73
	v_cvt_pk_bf16_f32 v197, v74, v75
	v_cvt_pk_bf16_f32 v198, v76, v77
	v_cvt_pk_bf16_f32 v199, v78, v79
	global_store_dwordx4 v52, v[192:195], s[66:67]
	global_store_dwordx4 v52, v[196:199], s[66:67] offset:16
	v_cvt_pk_bf16_f32 v200, v80, v81
	v_cvt_pk_bf16_f32 v201, v82, v83
	v_cvt_pk_bf16_f32 v202, v84, v85
	v_cvt_pk_bf16_f32 v203, v86, v87
	v_cvt_pk_bf16_f32 v204, v88, v89
	v_cvt_pk_bf16_f32 v205, v90, v91
	v_cvt_pk_bf16_f32 v206, v92, v93
	v_cvt_pk_bf16_f32 v207, v94, v95
	global_store_dwordx4 v53, v[200:203], s[66:67]
	global_store_dwordx4 v53, v[204:207], s[66:67] offset:16
	v_cvt_pk_bf16_f32 v208, v96, v97
	v_cvt_pk_bf16_f32 v209, v98, v99
	v_cvt_pk_bf16_f32 v210, v100, v101
	v_cvt_pk_bf16_f32 v211, v102, v103
	v_cvt_pk_bf16_f32 v212, v104, v105
	v_cvt_pk_bf16_f32 v213, v106, v107
	v_cvt_pk_bf16_f32 v214, v108, v109
	v_cvt_pk_bf16_f32 v215, v110, v111
	global_store_dwordx4 v54, v[208:211], s[66:67]
	global_store_dwordx4 v54, v[212:215], s[66:67] offset:16
	v_cvt_pk_bf16_f32 v216, v112, v113
	v_cvt_pk_bf16_f32 v217, v114, v115
	v_cvt_pk_bf16_f32 v218, v116, v117
	v_cvt_pk_bf16_f32 v219, v118, v119
	v_cvt_pk_bf16_f32 v220, v120, v121
	v_cvt_pk_bf16_f32 v221, v122, v123
	v_cvt_pk_bf16_f32 v222, v124, v125
	v_cvt_pk_bf16_f32 v223, v126, v127
	global_store_dwordx4 v55, v[216:219], s[66:67]
	global_store_dwordx4 v55, v[220:223], s[66:67] offset:16
	s_add_u32 s22, s22, s26
	s_cmp_lt_u32 s22, 0x8000
	s_cbranch_scc0 .Lgl1_done
	s_add_u32 s42, s22, s26
	s_min_u32 s42, s42, 0x7ffc
	s_lshl_b32 s30, s42, 12
	s_add_u32 s40, s16, s30
	s_addc_u32 s41, s17, 0
	global_load_dwordx4 v[64:67], v48, s[40:41]
	global_load_dwordx4 v[68:71], v48, s[40:41] offset:16
	global_load_dwordx4 v[72:75], v48, s[40:41] offset:32
	global_load_dwordx4 v[76:79], v48, s[40:41] offset:48
	global_load_dwordx4 v[80:83], v49, s[40:41]
	global_load_dwordx4 v[84:87], v49, s[40:41] offset:16
	global_load_dwordx4 v[88:91], v49, s[40:41] offset:32
	global_load_dwordx4 v[92:95], v49, s[40:41] offset:48
	global_load_dwordx4 v[96:99], v50, s[40:41]
	global_load_dwordx4 v[100:103], v50, s[40:41] offset:16
	global_load_dwordx4 v[104:107], v50, s[40:41] offset:32
	global_load_dwordx4 v[108:111], v50, s[40:41] offset:48
	global_load_dwordx4 v[112:115], v51, s[40:41]
	global_load_dwordx4 v[116:119], v51, s[40:41] offset:16
	global_load_dwordx4 v[120:123], v51, s[40:41] offset:32
	global_load_dwordx4 v[124:127], v51, s[40:41] offset:48
	s_lshl_b32 s30, s22, 12
	s_add_u32 s64, s14, s30
	s_addc_u32 s65, s15, 0
	s_lshl_b32 s30, s22, 11
	s_add_u32 s66, s18, s30
	s_addc_u32 s67, s19, 0
	s_waitcnt vmcnt(28)
	v_add_f32_e32 v56, v128, v129
	v_add_f32_e32 v56, v130, v56
	v_add_f32_e32 v56, v131, v56
	v_add_f32_e32 v56, v132, v56
	v_add_f32_e32 v56, v133, v56
	v_add_f32_e32 v56, v134, v56
	v_add_f32_e32 v56, v135, v56
	v_add_f32_e32 v56, v136, v56
	v_add_f32_e32 v56, v137, v56
	v_add_f32_e32 v56, v138, v56
	v_add_f32_e32 v56, v139, v56
	v_add_f32_e32 v56, v140, v56
	v_add_f32_e32 v56, v141, v56
	v_add_f32_e32 v56, v142, v56
	v_add_f32_e32 v56, v143, v56
	s_waitcnt vmcnt(24)
	v_add_f32_e32 v57, v144, v145
	v_add_f32_e32 v57, v146, v57
	v_add_f32_e32 v57, v147, v57
	v_add_f32_e32 v57, v148, v57
	v_add_f32_e32 v57, v149, v57
	v_add_f32_e32 v57, v150, v57
	v_add_f32_e32 v57, v151, v57
	v_add_f32_e32 v57, v152, v57
	v_add_f32_e32 v57, v153, v57
	v_add_f32_e32 v57, v154, v57
	v_add_f32_e32 v57, v155, v57
	v_add_f32_e32 v57, v156, v57
	v_add_f32_e32 v57, v157, v57
	v_add_f32_e32 v57, v158, v57
	v_add_f32_e32 v57, v159, v57
	s_waitcnt vmcnt(20)
	v_add_f32_e32 v58, v160, v161
	v_add_f32_e32 v58, v162, v58
	v_add_f32_e32 v58, v163, v58
	v_add_f32_e32 v58, v164, v58
	v_add_f32_e32 v58, v165, v58
	v_add_f32_e32 v58, v166, v58
	v_add_f32_e32 v58, v167, v58
	v_add_f32_e32 v58, v168, v58
	v_add_f32_e32 v58, v169, v58
	v_add_f32_e32 v58, v170, v58
	v_add_f32_e32 v58, v171, v58
	v_add_f32_e32 v58, v172, v58
	v_add_f32_e32 v58, v173, v58
	v_add_f32_e32 v58, v174, v58
	v_add_f32_e32 v58, v175, v58
	s_waitcnt vmcnt(16)
	v_add_f32_e32 v59, v176, v177
	v_add_f32_e32 v59, v178, v59
	v_add_f32_e32 v59, v179, v59
	v_add_f32_e32 v59, v180, v59
	v_add_f32_e32 v59, v181, v59
	v_add_f32_e32 v59, v182, v59
	v_add_f32_e32 v59, v183, v59
	v_add_f32_e32 v59, v184, v59
	v_add_f32_e32 v59, v185, v59
	v_add_f32_e32 v59, v186, v59
	v_add_f32_e32 v59, v187, v59
	v_add_f32_e32 v59, v188, v59
	v_add_f32_e32 v59, v189, v59
	v_add_f32_e32 v59, v190, v59
	v_add_f32_e32 v59, v191, v59
	ds_bpermute_b32 v60, v4, v56
	ds_bpermute_b32 v61, v4, v57
	ds_bpermute_b32 v62, v4, v58
	ds_bpermute_b32 v63, v4, v59
	s_waitcnt lgkmcnt(3)
	v_add_f32_e32 v56, v56, v60
	s_waitcnt lgkmcnt(2)
	v_add_f32_e32 v57, v57, v61
	s_waitcnt lgkmcnt(1)
	v_add_f32_e32 v58, v58, v62
	s_waitcnt lgkmcnt(0)
	v_add_f32_e32 v59, v59, v63
	ds_bpermute_b32 v60, v5, v56
	ds_bpermute_b32 v61, v5, v57
	ds_bpermute_b32 v62, v5, v58
	ds_bpermute_b32 v63, v5, v59
	s_waitcnt lgkmcnt(3)
	v_add_f32_e32 v56, v56, v60
	s_waitcnt lgkmcnt(2)
	v_add_f32_e32 v57, v57, v61
	s_waitcnt lgkmcnt(1)
	v_add_f32_e32 v58, v58, v62
	s_waitcnt lgkmcnt(0)
	v_add_f32_e32 v59, v59, v63
	ds_bpermute_b32 v60, v6, v56
	ds_bpermute_b32 v61, v6, v57
	ds_bpermute_b32 v62, v6, v58
	ds_bpermute_b32 v63, v6, v59
	s_waitcnt lgkmcnt(3)
	v_add_f32_e32 v56, v56, v60
	s_waitcnt lgkmcnt(2)
	v_add_f32_e32 v57, v57, v61
	s_waitcnt lgkmcnt(1)
	v_add_f32_e32 v58, v58, v62
	s_waitcnt lgkmcnt(0)
	v_add_f32_e32 v59, v59, v63
	ds_bpermute_b32 v60, v7, v56
	ds_bpermute_b32 v61, v7, v57
	ds_bpermute_b32 v62, v7, v58
	ds_bpermute_b32 v63, v7, v59
	s_waitcnt lgkmcnt(3)
	v_add_f32_e32 v56, v56, v60
	s_waitcnt lgkmcnt(2)
	v_add_f32_e32 v57, v57, v61
	s_waitcnt lgkmcnt(1)
	v_add_f32_e32 v58, v58, v62
	s_waitcnt lgkmcnt(0)
	v_add_f32_e32 v59, v59, v63
	ds_bpermute_b32 v60, v8, v56
	ds_bpermute_b32 v61, v8, v57
	ds_bpermute_b32 v62, v8, v58
	ds_bpermute_b32 v63, v8, v59
	s_waitcnt lgkmcnt(3)
	v_add_f32_e32 v56, v56, v60
	s_waitcnt lgkmcnt(2)
	v_add_f32_e32 v57, v57, v61
	s_waitcnt lgkmcnt(1)
	v_add_f32_e32 v58, v58, v62
	s_waitcnt lgkmcnt(0)
	v_add_f32_e32 v59, v59, v63
	ds_bpermute_b32 v60, v9, v56
	ds_bpermute_b32 v61, v9, v57
	ds_bpermute_b32 v62, v9, v58
	ds_bpermute_b32 v63, v9, v59
	s_waitcnt lgkmcnt(3)
	v_add_f32_e32 v56, v56, v60
	s_waitcnt lgkmcnt(2)
	v_add_f32_e32 v57, v57, v61
	s_waitcnt lgkmcnt(1)
	v_add_f32_e32 v58, v58, v62
	s_waitcnt lgkmcnt(0)
	v_add_f32_e32 v59, v59, v63
	v_mul_f32_e32 v60, 0x3a800000, v56
	v_sub_f32_e32 v128, v128, v60
	v_sub_f32_e32 v129, v129, v60
	v_sub_f32_e32 v130, v130, v60
	v_sub_f32_e32 v131, v131, v60
	v_sub_f32_e32 v132, v132, v60
	v_sub_f32_e32 v133, v133, v60
	v_sub_f32_e32 v134, v134, v60
	v_sub_f32_e32 v135, v135, v60
	v_sub_f32_e32 v136, v136, v60
	v_sub_f32_e32 v137, v137, v60
	v_sub_f32_e32 v138, v138, v60
	v_sub_f32_e32 v139, v139, v60
	v_sub_f32_e32 v140, v140, v60
	v_sub_f32_e32 v141, v141, v60
	v_sub_f32_e32 v142, v142, v60
	v_sub_f32_e32 v143, v143, v60
	v_mul_f32_e32 v56, v128, v128
	v_fmac_f32_e32 v56, v129, v129
	v_fmac_f32_e32 v56, v130, v130
	v_fmac_f32_e32 v56, v131, v131
	v_fmac_f32_e32 v56, v132, v132
	v_fmac_f32_e32 v56, v133, v133
	v_fmac_f32_e32 v56, v134, v134
	v_fmac_f32_e32 v56, v135, v135
	v_fmac_f32_e32 v56, v136, v136
	v_fmac_f32_e32 v56, v137, v137
	v_fmac_f32_e32 v56, v138, v138
	v_fmac_f32_e32 v56, v139, v139
	v_fmac_f32_e32 v56, v140, v140
	v_fmac_f32_e32 v56, v141, v141
	v_fmac_f32_e32 v56, v142, v142
	v_fmac_f32_e32 v56, v143, v143
	v_mul_f32_e32 v61, 0x3a800000, v57
	v_sub_f32_e32 v144, v144, v61
	v_sub_f32_e32 v145, v145, v61
	v_sub_f32_e32 v146, v146, v61
	v_sub_f32_e32 v147, v147, v61
	v_sub_f32_e32 v148, v148, v61
	v_sub_f32_e32 v149, v149, v61
	v_sub_f32_e32 v150, v150, v61
	v_sub_f32_e32 v151, v151, v61
	v_sub_f32_e32 v152, v152, v61
	v_sub_f32_e32 v153, v153, v61
	v_sub_f32_e32 v154, v154, v61
	v_sub_f32_e32 v155, v155, v61
	v_sub_f32_e32 v156, v156, v61
	v_sub_f32_e32 v157, v157, v61
	v_sub_f32_e32 v158, v158, v61
	v_sub_f32_e32 v159, v159, v61
	v_mul_f32_e32 v57, v144, v144
	v_fmac_f32_e32 v57, v145, v145
	v_fmac_f32_e32 v57, v146, v146
	v_fmac_f32_e32 v57, v147, v147
	v_fmac_f32_e32 v57, v148, v148
	v_fmac_f32_e32 v57, v149, v149
	v_fmac_f32_e32 v57, v150, v150
	v_fmac_f32_e32 v57, v151, v151
	v_fmac_f32_e32 v57, v152, v152
	v_fmac_f32_e32 v57, v153, v153
	v_fmac_f32_e32 v57, v154, v154
	v_fmac_f32_e32 v57, v155, v155
	v_fmac_f32_e32 v57, v156, v156
	v_fmac_f32_e32 v57, v157, v157
	v_fmac_f32_e32 v57, v158, v158
	v_fmac_f32_e32 v57, v159, v159
	v_mul_f32_e32 v62, 0x3a800000, v58
	v_sub_f32_e32 v160, v160, v62
	v_sub_f32_e32 v161, v161, v62
	v_sub_f32_e32 v162, v162, v62
	v_sub_f32_e32 v163, v163, v62
	v_sub_f32_e32 v164, v164, v62
	v_sub_f32_e32 v165, v165, v62
	v_sub_f32_e32 v166, v166, v62
	v_sub_f32_e32 v167, v167, v62
	v_sub_f32_e32 v168, v168, v62
	v_sub_f32_e32 v169, v169, v62
	v_sub_f32_e32 v170, v170, v62
	v_sub_f32_e32 v171, v171, v62
	v_sub_f32_e32 v172, v172, v62
	v_sub_f32_e32 v173, v173, v62
	v_sub_f32_e32 v174, v174, v62
	v_sub_f32_e32 v175, v175, v62
	v_mul_f32_e32 v58, v160, v160
	v_fmac_f32_e32 v58, v161, v161
	v_fmac_f32_e32 v58, v162, v162
	v_fmac_f32_e32 v58, v163, v163
	v_fmac_f32_e32 v58, v164, v164
	v_fmac_f32_e32 v58, v165, v165
	v_fmac_f32_e32 v58, v166, v166
	v_fmac_f32_e32 v58, v167, v167
	v_fmac_f32_e32 v58, v168, v168
	v_fmac_f32_e32 v58, v169, v169
	v_fmac_f32_e32 v58, v170, v170
	v_fmac_f32_e32 v58, v171, v171
	v_fmac_f32_e32 v58, v172, v172
	v_fmac_f32_e32 v58, v173, v173
	v_fmac_f32_e32 v58, v174, v174
	v_fmac_f32_e32 v58, v175, v175
	v_mul_f32_e32 v63, 0x3a800000, v59
	v_sub_f32_e32 v176, v176, v63
	v_sub_f32_e32 v177, v177, v63
	v_sub_f32_e32 v178, v178, v63
	v_sub_f32_e32 v179, v179, v63
	v_sub_f32_e32 v180, v180, v63
	v_sub_f32_e32 v181, v181, v63
	v_sub_f32_e32 v182, v182, v63
	v_sub_f32_e32 v183, v183, v63
	v_sub_f32_e32 v184, v184, v63
	v_sub_f32_e32 v185, v185, v63
	v_sub_f32_e32 v186, v186, v63
	v_sub_f32_e32 v187, v187, v63
	v_sub_f32_e32 v188, v188, v63
	v_sub_f32_e32 v189, v189, v63
	v_sub_f32_e32 v190, v190, v63
	v_sub_f32_e32 v191, v191, v63
	v_mul_f32_e32 v59, v176, v176
	v_fmac_f32_e32 v59, v177, v177
	v_fmac_f32_e32 v59, v178, v178
	v_fmac_f32_e32 v59, v179, v179
	v_fmac_f32_e32 v59, v180, v180
	v_fmac_f32_e32 v59, v181, v181
	v_fmac_f32_e32 v59, v182, v182
	v_fmac_f32_e32 v59, v183, v183
	v_fmac_f32_e32 v59, v184, v184
	v_fmac_f32_e32 v59, v185, v185
	v_fmac_f32_e32 v59, v186, v186
	v_fmac_f32_e32 v59, v187, v187
	v_fmac_f32_e32 v59, v188, v188
	v_fmac_f32_e32 v59, v189, v189
	v_fmac_f32_e32 v59, v190, v190
	v_fmac_f32_e32 v59, v191, v191
	ds_bpermute_b32 v60, v4, v56
	ds_bpermute_b32 v61, v4, v57
	ds_bpermute_b32 v62, v4, v58
	ds_bpermute_b32 v63, v4, v59
	s_waitcnt lgkmcnt(3)
	v_add_f32_e32 v56, v56, v60
	s_waitcnt lgkmcnt(2)
	v_add_f32_e32 v57, v57, v61
	s_waitcnt lgkmcnt(1)
	v_add_f32_e32 v58, v58, v62
	s_waitcnt lgkmcnt(0)
	v_add_f32_e32 v59, v59, v63
	ds_bpermute_b32 v60, v5, v56
	ds_bpermute_b32 v61, v5, v57
	ds_bpermute_b32 v62, v5, v58
	ds_bpermute_b32 v63, v5, v59
	s_waitcnt lgkmcnt(3)
	v_add_f32_e32 v56, v56, v60
	s_waitcnt lgkmcnt(2)
	v_add_f32_e32 v57, v57, v61
	s_waitcnt lgkmcnt(1)
	v_add_f32_e32 v58, v58, v62
	s_waitcnt lgkmcnt(0)
	v_add_f32_e32 v59, v59, v63
	ds_bpermute_b32 v60, v6, v56
	ds_bpermute_b32 v61, v6, v57
	ds_bpermute_b32 v62, v6, v58
	ds_bpermute_b32 v63, v6, v59
	s_waitcnt lgkmcnt(3)
	v_add_f32_e32 v56, v56, v60
	s_waitcnt lgkmcnt(2)
	v_add_f32_e32 v57, v57, v61
	s_waitcnt lgkmcnt(1)
	v_add_f32_e32 v58, v58, v62
	s_waitcnt lgkmcnt(0)
	v_add_f32_e32 v59, v59, v63
	ds_bpermute_b32 v60, v7, v56
	ds_bpermute_b32 v61, v7, v57
	ds_bpermute_b32 v62, v7, v58
	ds_bpermute_b32 v63, v7, v59
	s_waitcnt lgkmcnt(3)
	v_add_f32_e32 v56, v56, v60
	s_waitcnt lgkmcnt(2)
	v_add_f32_e32 v57, v57, v61
	s_waitcnt lgkmcnt(1)
	v_add_f32_e32 v58, v58, v62
	s_waitcnt lgkmcnt(0)
	v_add_f32_e32 v59, v59, v63
	ds_bpermute_b32 v60, v8, v56
	ds_bpermute_b32 v61, v8, v57
	ds_bpermute_b32 v62, v8, v58
	ds_bpermute_b32 v63, v8, v59
	s_waitcnt lgkmcnt(3)
	v_add_f32_e32 v56, v56, v60
	s_waitcnt lgkmcnt(2)
	v_add_f32_e32 v57, v57, v61
	s_waitcnt lgkmcnt(1)
	v_add_f32_e32 v58, v58, v62
	s_waitcnt lgkmcnt(0)
	v_add_f32_e32 v59, v59, v63
	ds_bpermute_b32 v60, v9, v56
	ds_bpermute_b32 v61, v9, v57
	ds_bpermute_b32 v62, v9, v58
	ds_bpermute_b32 v63, v9, v59
	s_waitcnt lgkmcnt(3)
	v_add_f32_e32 v56, v56, v60
	s_waitcnt lgkmcnt(2)
	v_add_f32_e32 v57, v57, v61
	s_waitcnt lgkmcnt(1)
	v_add_f32_e32 v58, v58, v62
	s_waitcnt lgkmcnt(0)
	v_add_f32_e32 v59, v59, v63
	v_fmamk_f32 v56, v56, 0x3a800000, v10
	v_fmamk_f32 v57, v57, 0x3a800000, v10
	v_fmamk_f32 v58, v58, 0x3a800000, v10
	v_fmamk_f32 v59, v59, 0x3a800000, v10
	v_rsq_f32_e32 v56, v56
	v_rsq_f32_e32 v57, v57
	v_rsq_f32_e32 v58, v58
	v_rsq_f32_e32 v59, v59
	s_nop 1
	v_mul_f32_e32 v128, v128, v56
	v_mul_f32_e32 v129, v129, v56
	v_mul_f32_e32 v130, v130, v56
	v_mul_f32_e32 v131, v131, v56
	v_mul_f32_e32 v132, v132, v56
	v_mul_f32_e32 v133, v133, v56
	v_mul_f32_e32 v134, v134, v56
	v_mul_f32_e32 v135, v135, v56
	v_mul_f32_e32 v136, v136, v56
	v_mul_f32_e32 v137, v137, v56
	v_mul_f32_e32 v138, v138, v56
	v_mul_f32_e32 v139, v139, v56
	v_mul_f32_e32 v140, v140, v56
	v_mul_f32_e32 v141, v141, v56
	v_mul_f32_e32 v142, v142, v56
	v_mul_f32_e32 v143, v143, v56
	v_fma_f32 v128, v128, v16, v32
	v_fma_f32 v129, v129, v17, v33
	v_fma_f32 v130, v130, v18, v34
	v_fma_f32 v131, v131, v19, v35
	v_fma_f32 v132, v132, v20, v36
	v_fma_f32 v133, v133, v21, v37
	v_fma_f32 v134, v134, v22, v38
	v_fma_f32 v135, v135, v23, v39
	v_fma_f32 v136, v136, v24, v40
	v_fma_f32 v137, v137, v25, v41
	v_fma_f32 v138, v138, v26, v42
	v_fma_f32 v139, v139, v27, v43
	v_fma_f32 v140, v140, v28, v44
	v_fma_f32 v141, v141, v29, v45
	v_fma_f32 v142, v142, v30, v46
	v_fma_f32 v143, v143, v31, v47
	global_store_dwordx4 v48, v[128:131], s[64:65]
	global_store_dwordx4 v48, v[132:135], s[64:65] offset:16
	global_store_dwordx4 v48, v[136:139], s[64:65] offset:32
	global_store_dwordx4 v48, v[140:143], s[64:65] offset:48
	v_mul_f32_e32 v144, v144, v57
	v_mul_f32_e32 v145, v145, v57
	v_mul_f32_e32 v146, v146, v57
	v_mul_f32_e32 v147, v147, v57
	v_mul_f32_e32 v148, v148, v57
	v_mul_f32_e32 v149, v149, v57
	v_mul_f32_e32 v150, v150, v57
	v_mul_f32_e32 v151, v151, v57
	v_mul_f32_e32 v152, v152, v57
	v_mul_f32_e32 v153, v153, v57
	v_mul_f32_e32 v154, v154, v57
	v_mul_f32_e32 v155, v155, v57
	v_mul_f32_e32 v156, v156, v57
	v_mul_f32_e32 v157, v157, v57
	v_mul_f32_e32 v158, v158, v57
	v_mul_f32_e32 v159, v159, v57
	v_fma_f32 v144, v144, v16, v32
	v_fma_f32 v145, v145, v17, v33
	v_fma_f32 v146, v146, v18, v34
	v_fma_f32 v147, v147, v19, v35
	v_fma_f32 v148, v148, v20, v36
	v_fma_f32 v149, v149, v21, v37
	v_fma_f32 v150, v150, v22, v38
	v_fma_f32 v151, v151, v23, v39
	v_fma_f32 v152, v152, v24, v40
	v_fma_f32 v153, v153, v25, v41
	v_fma_f32 v154, v154, v26, v42
	v_fma_f32 v155, v155, v27, v43
	v_fma_f32 v156, v156, v28, v44
	v_fma_f32 v157, v157, v29, v45
	v_fma_f32 v158, v158, v30, v46
	v_fma_f32 v159, v159, v31, v47
	global_store_dwordx4 v49, v[144:147], s[64:65]
	global_store_dwordx4 v49, v[148:151], s[64:65] offset:16
	global_store_dwordx4 v49, v[152:155], s[64:65] offset:32
	global_store_dwordx4 v49, v[156:159], s[64:65] offset:48
	v_mul_f32_e32 v160, v160, v58
	v_mul_f32_e32 v161, v161, v58
	v_mul_f32_e32 v162, v162, v58
	v_mul_f32_e32 v163, v163, v58
	v_mul_f32_e32 v164, v164, v58
	v_mul_f32_e32 v165, v165, v58
	v_mul_f32_e32 v166, v166, v58
	v_mul_f32_e32 v167, v167, v58
	v_mul_f32_e32 v168, v168, v58
	v_mul_f32_e32 v169, v169, v58
	v_mul_f32_e32 v170, v170, v58
	v_mul_f32_e32 v171, v171, v58
	v_mul_f32_e32 v172, v172, v58
	v_mul_f32_e32 v173, v173, v58
	v_mul_f32_e32 v174, v174, v58
	v_mul_f32_e32 v175, v175, v58
	v_fma_f32 v160, v160, v16, v32
	v_fma_f32 v161, v161, v17, v33
	v_fma_f32 v162, v162, v18, v34
	v_fma_f32 v163, v163, v19, v35
	v_fma_f32 v164, v164, v20, v36
	v_fma_f32 v165, v165, v21, v37
	v_fma_f32 v166, v166, v22, v38
	v_fma_f32 v167, v167, v23, v39
	v_fma_f32 v168, v168, v24, v40
	v_fma_f32 v169, v169, v25, v41
	v_fma_f32 v170, v170, v26, v42
	v_fma_f32 v171, v171, v27, v43
	v_fma_f32 v172, v172, v28, v44
	v_fma_f32 v173, v173, v29, v45
	v_fma_f32 v174, v174, v30, v46
	v_fma_f32 v175, v175, v31, v47
	global_store_dwordx4 v50, v[160:163], s[64:65]
	global_store_dwordx4 v50, v[164:167], s[64:65] offset:16
	global_store_dwordx4 v50, v[168:171], s[64:65] offset:32
	global_store_dwordx4 v50, v[172:175], s[64:65] offset:48
	v_mul_f32_e32 v176, v176, v59
	v_mul_f32_e32 v177, v177, v59
	v_mul_f32_e32 v178, v178, v59
	v_mul_f32_e32 v179, v179, v59
	v_mul_f32_e32 v180, v180, v59
	v_mul_f32_e32 v181, v181, v59
	v_mul_f32_e32 v182, v182, v59
	v_mul_f32_e32 v183, v183, v59
	v_mul_f32_e32 v184, v184, v59
	v_mul_f32_e32 v185, v185, v59
	v_mul_f32_e32 v186, v186, v59
	v_mul_f32_e32 v187, v187, v59
	v_mul_f32_e32 v188, v188, v59
	v_mul_f32_e32 v189, v189, v59
	v_mul_f32_e32 v190, v190, v59
	v_mul_f32_e32 v191, v191, v59
	v_fma_f32 v176, v176, v16, v32
	v_fma_f32 v177, v177, v17, v33
	v_fma_f32 v178, v178, v18, v34
	v_fma_f32 v179, v179, v19, v35
	v_fma_f32 v180, v180, v20, v36
	v_fma_f32 v181, v181, v21, v37
	v_fma_f32 v182, v182, v22, v38
	v_fma_f32 v183, v183, v23, v39
	v_fma_f32 v184, v184, v24, v40
	v_fma_f32 v185, v185, v25, v41
	v_fma_f32 v186, v186, v26, v42
	v_fma_f32 v187, v187, v27, v43
	v_fma_f32 v188, v188, v28, v44
	v_fma_f32 v189, v189, v29, v45
	v_fma_f32 v190, v190, v30, v46
	v_fma_f32 v191, v191, v31, v47
	global_store_dwordx4 v51, v[176:179], s[64:65]
	global_store_dwordx4 v51, v[180:183], s[64:65] offset:16
	global_store_dwordx4 v51, v[184:187], s[64:65] offset:32
	global_store_dwordx4 v51, v[188:191], s[64:65] offset:48
	s_nop 1
	v_cvt_pk_bf16_f32 v192, v128, v129
	v_cvt_pk_bf16_f32 v193, v130, v131
	v_cvt_pk_bf16_f32 v194, v132, v133
	v_cvt_pk_bf16_f32 v195, v134, v135
	v_cvt_pk_bf16_f32 v196, v136, v137
	v_cvt_pk_bf16_f32 v197, v138, v139
	v_cvt_pk_bf16_f32 v198, v140, v141
	v_cvt_pk_bf16_f32 v199, v142, v143
	global_store_dwordx4 v52, v[192:195], s[66:67]
	global_store_dwordx4 v52, v[196:199], s[66:67] offset:16
	v_cvt_pk_bf16_f32 v200, v144, v145
	v_cvt_pk_bf16_f32 v201, v146, v147
	v_cvt_pk_bf16_f32 v202, v148, v149
	v_cvt_pk_bf16_f32 v203, v150, v151
	v_cvt_pk_bf16_f32 v204, v152, v153
	v_cvt_pk_bf16_f32 v205, v154, v155
	v_cvt_pk_bf16_f32 v206, v156, v157
	v_cvt_pk_bf16_f32 v207, v158, v159
	global_store_dwordx4 v53, v[200:203], s[66:67]
	global_store_dwordx4 v53, v[204:207], s[66:67] offset:16
	v_cvt_pk_bf16_f32 v208, v160, v161
	v_cvt_pk_bf16_f32 v209, v162, v163
	v_cvt_pk_bf16_f32 v210, v164, v165
	v_cvt_pk_bf16_f32 v211, v166, v167
	v_cvt_pk_bf16_f32 v212, v168, v169
	v_cvt_pk_bf16_f32 v213, v170, v171
	v_cvt_pk_bf16_f32 v214, v172, v173
	v_cvt_pk_bf16_f32 v215, v174, v175
	global_store_dwordx4 v54, v[208:211], s[66:67]
	global_store_dwordx4 v54, v[212:215], s[66:67] offset:16
	v_cvt_pk_bf16_f32 v216, v176, v177
	v_cvt_pk_bf16_f32 v217, v178, v179
	v_cvt_pk_bf16_f32 v218, v180, v181
	v_cvt_pk_bf16_f32 v219, v182, v183
	v_cvt_pk_bf16_f32 v220, v184, v185
	v_cvt_pk_bf16_f32 v221, v186, v187
	v_cvt_pk_bf16_f32 v222, v188, v189
	v_cvt_pk_bf16_f32 v223, v190, v191
	global_store_dwordx4 v55, v[216:219], s[66:67]
	global_store_dwordx4 v55, v[220:223], s[66:67] offset:16
	s_add_u32 s22, s22, s26
	s_cmp_lt_u32 s22, 0x8000
	s_cbranch_scc1 .Lgl1_loop

.Lgl2_entry:
	s_mov_b64 s[82:83], exec
	v_readlane_b32 s4, v254, 40
	v_readlane_b32 s5, v254, 41
	v_readlane_b32 s6, v255, 15
	v_readlane_b32 s7, v254, 21
	s_nop 4
	s_load_dword s8, s[4:5], 0x0
	v_mbcnt_lo_u32_b32 v0, -1, 0
	v_mbcnt_hi_u32_b32 v0, -1, v0
	v_readlane_b32 s9, v255, 48
	v_readlane_b32 s10, v255, 52
	v_readlane_b32 s11, v255, 53
	v_readlane_b32 s12, v255, 54
	v_readlane_b32 s13, v255, 55
	v_readlane_b32 s14, v255, 50
	v_readlane_b32 s15, v255, 51
	v_lshlrev_b32_e32 v1, 6, v0
	v_lshlrev_b32_e32 v2, 5, v0
	v_lshlrev_b32_e32 v3, 2, v0
	v_xor_b32_e32 v4, 0x4, v3
	v_xor_b32_e32 v5, 0x8, v3
	v_xor_b32_e32 v6, 0x10, v3
	v_xor_b32_e32 v7, 0x20, v3
	v_xor_b32_e32 v8, 0x40, v3
	v_xor_b32_e32 v9, 0x80, v3
	v_mov_b32_e32 v10, 0x3727c5ac
	s_and_b32 s9, s9, 0xff
	s_lshl_b32 s9, s9, 13
	s_add_u32 s9, s9, 0x1000
	s_add_u32 s10, s10, s9
	s_addc_u32 s11, s11, 0
	s_add_u32 s12, s12, s9
	s_addc_u32 s13, s13, 0
	global_load_dwordx4 v[16:19], v1, s[10:11]
	global_load_dwordx4 v[20:23], v1, s[10:11] offset:16
	global_load_dwordx4 v[24:27], v1, s[10:11] offset:32
	global_load_dwordx4 v[28:31], v1, s[10:11] offset:48
	global_load_dwordx4 v[32:35], v1, s[12:13]
	global_load_dwordx4 v[36:39], v1, s[12:13] offset:16
	global_load_dwordx4 v[40:43], v1, s[12:13] offset:32
	global_load_dwordx4 v[44:47], v1, s[12:13] offset:48
	v_add_u32_e32 v49, 0x1000, v1
	v_add_u32_e32 v53, 0x800, v2
	v_add_u32_e32 v50, 0x2000, v1
	v_add_u32_e32 v54, 0x1000, v2
	v_add_u32_e32 v51, 0x3000, v1
	v_add_u32_e32 v55, 0x1800, v2
	v_mov_b32_e32 v48, v1
	v_mov_b32_e32 v52, v2
	s_lshl_b32 s6, s6, 2
	s_lshr_b32 s7, s7, 6
	s_add_u32 s6, s6, s7
	s_lshl_b32 s22, s6, 2
	s_waitcnt lgkmcnt(0)
	s_lshl_b32 s26, s8, 4
	s_add_u32 s16, s92, 0x2a100000
	s_addc_u32 s17, s93, 0
	s_add_u32 s18, s92, 0x8100000
	s_addc_u32 s19, s93, 0
	s_cmp_ge_u32 s22, 0x8000
	s_cbranch_scc1 .Lgl2_done
	s_lshl_b32 s30, s22, 12
	s_add_u32 s40, s16, s30
	s_addc_u32 s41, s17, 0
	global_load_dwordx4 v[64:67], v48, s[40:41]
	global_load_dwordx4 v[68:71], v48, s[40:41] offset:16
	global_load_dwordx4 v[72:75], v48, s[40:41] offset:32
	global_load_dwordx4 v[76:79], v48, s[40:41] offset:48
	global_load_dwordx4 v[80:83], v49, s[40:41]
	global_load_dwordx4 v[84:87], v49, s[40:41] offset:16
	global_load_dwordx4 v[88:91], v49, s[40:41] offset:32
	global_load_dwordx4 v[92:95], v49, s[40:41] offset:48
	global_load_dwordx4 v[96:99], v50, s[40:41]
	global_load_dwordx4 v[100:103], v50, s[40:41] offset:16
	global_load_dwordx4 v[104:107], v50, s[40:41] offset:32
	global_load_dwordx4 v[108:111], v50, s[40:41] offset:48
	global_load_dwordx4 v[112:115], v51, s[40:41]
	global_load_dwordx4 v[116:119], v51, s[40:41] offset:16
	global_load_dwordx4 v[120:123], v51, s[40:41] offset:32
	global_load_dwordx4 v[124:127], v51, s[40:41] offset:48
	s_waitcnt vmcnt(16)
